# scan y-reduction: one conservative wait state before two DPP adds whose plain source was written one instruction earlier (timing-neutral hardening)
# baseline (speedup 1.0000x reference)
; #define LAS __attribute__((address_space(3)))
; __device__ __forceinline__ float sum16(float x) { x += dpp_f<0xB1>(x); x += dpp_f<0x4E>(x); x += dpp_f<0x141>(x); x += dpp_f<0x140>(x); return x; }
; __device__ __forceinline__ void rwkv_scan_phase(LAS unsigned char* lds, const bf16_t* RKV, const float* DEC, const float* AF, const float* k_k, const float* k_a, const float* r_k, float* BON, float* Y, int bx, const int tid) {
;     ...
;             const LAS unsigned char* base = lds + (c & 1) * SC_BUF + ks4; const LAS unsigned char* vbase = lds + (c & 1) * SC_BUF + 768 + rowi * 4;
;             f32x4 r4 = *(const LAS f32x4*)(base), w4 = *(const LAS f32x4*)(base + 256), k4 = *(const LAS f32x4*)(base + 512), a4 = *(const LAS f32x4*)(base + 1024), b4 = *(const LAS f32x4*)(base + 1280);
;             float vv = *(const LAS float*)(vbase); float ykeep = 0.f;
; #pragma unroll
;             for (int t = 0; t < SC_T; ++t) {
;                 f32x4 r4n = r4, w4n = w4, k4n = k4, a4n = a4, b4n = b4; float vvn = vv;
;                 if (t + 1 < SC_T) { const LAS unsigned char* p = base + (t + 1) * SC_TOK;
;                     r4n = *(const LAS f32x4*)(p); w4n = *(const LAS f32x4*)(p + 256); k4n = *(const LAS f32x4*)(p + 512); a4n = *(const LAS f32x4*)(p + 1024); b4n = *(const LAS f32x4*)(p + 1280);
;                     vvn = *(const LAS float*)(vbase + (t + 1) * SC_TOK); }
;                 const f32x2 a01 = {a4[0], a4[1]}, a23 = {a4[2], a4[3]}, w01 = {w4[0], w4[1]}, w23 = {w4[2], w4[3]}, b01 = {b4[0], b4[1]}, b23 = {b4[2], b4[3]}, k01 = {k4[0], k4[1]}, k23 = {k4[2], k4[3]}, r01 = {r4[0], r4[1]}, r23 = {r4[2], r4[3]};
;                 const f32x2 tsa = S01 * a01 + S23 * a23; const float sa = sum16(tsa[0] + tsa[1]);
;                 S01 = S01 * w01 + (b01 * sa + k01 * vv); S23 = S23 * w23 + (b23 * sa + k23 * vv);
;                 const f32x2 ty = S01 * r01 + S23 * r23; const float y = sum16(ty[0] + ty[1]);
;                 ykeep = ((lane & 15) == (t & 15)) ? y : ykeep;
;                 if ((t & 15) == 15) yp[(size_t)(c * SC_T + (t - 15) + (lane & 15)) * 2048] = ykeep;
.LBB0_224:
	v_readlane_b32 s52, v255, 42
	v_readlane_b32 s53, v255, 43
	s_add_i32 s35, s21, -1
	s_mov_b64 s[76:77], -1
	s_and_b64 vcc, exec, s[52:53]
	s_cbranch_vccz .LBB0_226
	s_bitcmp1_b32 s35, 0
	s_cselect_b32 s52, 0xc000, 0
	v_add_u32_e32 v50, s52, v106
	v_add_u32_e32 v51, s52, v107
	ds_read_b128 v[0:3], v50 offset:1024
	ds_read_b128 v[8:11], v50 offset:512
	ds_read2st64_b32 v[40:41], v51 offset0:3 offset1:9
	ds_read_b128 v[4:7], v50 offset:256
	ds_read_b128 v[12:15], v50 offset:1280
	ds_read_b128 v[16:19], v50
	ds_read_b128 v[20:23], v50 offset:2560
	s_mov_b32 s40, 0xaaaaaaaa
	s_mov_b32 s41, 0xaaaaaaaa
	s_mov_b32 s46, 0xcccccccc
	s_mov_b32 s47, 0xcccccccc
	s_mov_b64 s[76:77], 0x20000
	s_waitcnt lgkmcnt(0)
	v_mul_f32_e32 v48, v94, v0
	v_fmac_f32_e32 v48, v95, v1
	v_fmac_f32_e32 v48, v96, v2
	v_fmac_f32_e32 v48, v97, v3
	ds_read_b128 v[0:3], v50 offset:4096
	ds_read_b128 v[28:31], v50 offset:2048
	ds_read_b128 v[24:27], v50 offset:1792
	v_add_f32_dpp v48, v48, v48 quad_perm:[1,0,3,2] row_mask:0xf bank_mask:0xf bound_ctrl:1
	v_pk_mul_f32 v[44:45], v[8:9], v[40:41] op_sel_hi:[1,0]
	v_pk_mul_f32 v[46:47], v[10:11], v[40:41] op_sel_hi:[1,0]
	v_add_f32_dpp v48, v48, v48 quad_perm:[2,3,0,1] row_mask:0xf bank_mask:0xf bound_ctrl:1
	v_pk_fma_f32 v[44:45], v[94:95], v[4:5], v[44:45]
	v_pk_fma_f32 v[46:47], v[96:97], v[6:7], v[46:47]
	v_add_f32_dpp v48, v48, v48 row_half_mirror row_mask:0xf bank_mask:0xf bound_ctrl:1
	ds_read_b128 v[32:35], v50 offset:2816
	ds_read_b128 v[36:39], v50 offset:1536
	v_add_f32_dpp v48, v48, v48 row_mirror row_mask:0xf bank_mask:0xf bound_ctrl:1
	v_pk_fma_f32 v[44:45], v[12:13], v[48:49], v[44:45] op_sel_hi:[1,0,1]
	v_pk_fma_f32 v[46:47], v[14:15], v[48:49], v[46:47] op_sel_hi:[1,0,1]
	v_pk_mul_f32 v[48:49], v[44:45], v[20:21]
	v_pk_mul_f32 v[76:77], v[44:45], v[16:17]
	v_pk_fma_f32 v[48:49], v[46:47], v[22:23], v[48:49]
	v_pk_fma_f32 v[76:77], v[46:47], v[18:19], v[76:77]
	v_add_f32_e32 v48, v48, v49
	v_add_f32_e32 v60, v76, v77
	ds_read_b128 v[20:23], v50 offset:5632
	ds_read_b128 v[8:11], v50 offset:3584
	ds_read2st64_b32 v[42:43], v51 offset0:15 offset1:21
	ds_read_b128 v[4:7], v50 offset:3328
	s_waitcnt lgkmcnt(4)
	v_add_f32_dpp v48, v48, v48 quad_perm:[1,0,3,2] row_mask:0xf bank_mask:0xf bound_ctrl:1
	v_pk_mul_f32 v[94:95], v[28:29], v[40:41] op_sel:[0,1]
	v_pk_mul_f32 v[96:97], v[30:31], v[40:41] op_sel:[0,1]
	v_add_f32_dpp v48, v48, v48 quad_perm:[2,3,0,1] row_mask:0xf bank_mask:0xf bound_ctrl:1
	v_pk_fma_f32 v[94:95], v[44:45], v[24:25], v[94:95]
	v_pk_fma_f32 v[96:97], v[46:47], v[26:27], v[96:97]
	v_add_f32_dpp v48, v48, v48 row_half_mirror row_mask:0xf bank_mask:0xf bound_ctrl:1
	ds_read_b128 v[12:15], v50 offset:4352
	ds_read_b128 v[16:19], v50 offset:3072
	v_add_f32_dpp v48, v48, v48 row_mirror row_mask:0xf bank_mask:0xf bound_ctrl:1
	v_pk_fma_f32 v[94:95], v[32:33], v[48:49], v[94:95] op_sel_hi:[1,0,1]
	v_pk_fma_f32 v[96:97], v[34:35], v[48:49], v[96:97] op_sel_hi:[1,0,1]
	v_pk_mul_f32 v[48:49], v[94:95], v[0:1]
	v_pk_mul_f32 v[76:77], v[94:95], v[36:37]
	v_pk_fma_f32 v[48:49], v[96:97], v[2:3], v[48:49]
	v_pk_fma_f32 v[76:77], v[96:97], v[38:39], v[76:77]
	v_add_f32_e32 v48, v48, v49
	v_add_f32_e32 v61, v76, v77
	ds_read_b128 v[0:3], v50 offset:7168
	ds_read_b128 v[28:31], v50 offset:5120
	ds_read_b128 v[24:27], v50 offset:4864
	s_waitcnt lgkmcnt(3)
	v_add_f32_dpp v48, v48, v48 quad_perm:[1,0,3,2] row_mask:0xf bank_mask:0xf bound_ctrl:1
	v_pk_mul_f32 v[44:45], v[8:9], v[42:43] op_sel_hi:[1,0]
	v_pk_mul_f32 v[46:47], v[10:11], v[42:43] op_sel_hi:[1,0]
	v_add_f32_dpp v48, v48, v48 quad_perm:[2,3,0,1] row_mask:0xf bank_mask:0xf bound_ctrl:1
	v_pk_fma_f32 v[44:45], v[94:95], v[4:5], v[44:45]
	v_pk_fma_f32 v[46:47], v[96:97], v[6:7], v[46:47]
	v_add_f32_dpp v48, v48, v48 row_half_mirror row_mask:0xf bank_mask:0xf bound_ctrl:1
	ds_read_b128 v[32:35], v50 offset:5888
	ds_read_b128 v[36:39], v50 offset:4608
	v_add_f32_dpp v48, v48, v48 row_mirror row_mask:0xf bank_mask:0xf bound_ctrl:1
	v_pk_fma_f32 v[44:45], v[12:13], v[48:49], v[44:45] op_sel_hi:[1,0,1]
	v_pk_fma_f32 v[46:47], v[14:15], v[48:49], v[46:47] op_sel_hi:[1,0,1]
	v_pk_mul_f32 v[48:49], v[44:45], v[20:21]
	v_pk_mul_f32 v[76:77], v[44:45], v[16:17]
	v_pk_fma_f32 v[48:49], v[46:47], v[22:23], v[48:49]
	v_pk_fma_f32 v[76:77], v[46:47], v[18:19], v[76:77]
	v_add_f32_e32 v48, v48, v49
	v_add_f32_e32 v62, v76, v77
	ds_read_b128 v[20:23], v50 offset:8704
	ds_read_b128 v[8:11], v50 offset:6656
	ds_read2st64_b32 v[40:41], v51 offset0:27 offset1:33
	ds_read_b128 v[4:7], v50 offset:6400
	s_waitcnt lgkmcnt(4)
	v_add_f32_dpp v48, v48, v48 quad_perm:[1,0,3,2] row_mask:0xf bank_mask:0xf bound_ctrl:1
	v_pk_mul_f32 v[94:95], v[28:29], v[42:43] op_sel:[0,1]
	v_pk_mul_f32 v[96:97], v[30:31], v[42:43] op_sel:[0,1]
	v_add_f32_dpp v48, v48, v48 quad_perm:[2,3,0,1] row_mask:0xf bank_mask:0xf bound_ctrl:1
	v_pk_fma_f32 v[94:95], v[44:45], v[24:25], v[94:95]
	v_pk_fma_f32 v[96:97], v[46:47], v[26:27], v[96:97]
	v_add_f32_dpp v48, v48, v48 row_half_mirror row_mask:0xf bank_mask:0xf bound_ctrl:1
	ds_read_b128 v[12:15], v50 offset:7424
	ds_read_b128 v[16:19], v50 offset:6144
	v_add_f32_dpp v48, v48, v48 row_mirror row_mask:0xf bank_mask:0xf bound_ctrl:1
	v_pk_fma_f32 v[94:95], v[32:33], v[48:49], v[94:95] op_sel_hi:[1,0,1]
	v_pk_fma_f32 v[96:97], v[34:35], v[48:49], v[96:97] op_sel_hi:[1,0,1]
	v_pk_mul_f32 v[48:49], v[94:95], v[0:1]
	v_pk_mul_f32 v[76:77], v[94:95], v[36:37]
	v_pk_fma_f32 v[48:49], v[96:97], v[2:3], v[48:49]
	v_pk_fma_f32 v[76:77], v[96:97], v[38:39], v[76:77]
	v_add_f32_e32 v48, v48, v49
	v_add_f32_e32 v63, v76, v77
	ds_read_b128 v[0:3], v50 offset:10240
	ds_read_b128 v[28:31], v50 offset:8192
	ds_read_b128 v[24:27], v50 offset:7936
	s_waitcnt lgkmcnt(3)
; #define LAS __attribute__((address_space(3)))
; __device__ __forceinline__ float sum16(float x) { x += dpp_f<0xB1>(x); x += dpp_f<0x4E>(x); x += dpp_f<0x141>(x); x += dpp_f<0x140>(x); return x; }
; __device__ __forceinline__ void rwkv_scan_phase(LAS unsigned char* lds, const bf16_t* RKV, const float* DEC, const float* AF, const float* k_k, const float* k_a, const float* r_k, float* BON, float* Y, int bx, const int tid) {
;     ...
;             for (int t = 0; t < SC_T; ++t) {
;                 f32x4 r4n = r4, w4n = w4, k4n = k4, a4n = a4, b4n = b4; float vvn = vv;
;                 if (t + 1 < SC_T) { const LAS unsigned char* p = base + (t + 1) * SC_TOK;
;                     r4n = *(const LAS f32x4*)(p); w4n = *(const LAS f32x4*)(p + 256); k4n = *(const LAS f32x4*)(p + 512); a4n = *(const LAS f32x4*)(p + 1024); b4n = *(const LAS f32x4*)(p + 1280);
;                     vvn = *(const LAS float*)(vbase + (t + 1) * SC_TOK); }
;                 const f32x2 a01 = {a4[0], a4[1]}, a23 = {a4[2], a4[3]}, w01 = {w4[0], w4[1]}, w23 = {w4[2], w4[3]}, b01 = {b4[0], b4[1]}, b23 = {b4[2], b4[3]}, k01 = {k4[0], k4[1]}, k23 = {k4[2], k4[3]}, r01 = {r4[0], r4[1]}, r23 = {r4[2], r4[3]};
;                 const f32x2 tsa = S01 * a01 + S23 * a23; const float sa = sum16(tsa[0] + tsa[1]);
;                 S01 = S01 * w01 + (b01 * sa + k01 * vv); S23 = S23 * w23 + (b23 * sa + k23 * vv);
;                 const f32x2 ty = S01 * r01 + S23 * r23; const float y = sum16(ty[0] + ty[1]);
	v_add_f32_dpp v48, v48, v48 quad_perm:[1,0,3,2] row_mask:0xf bank_mask:0xf bound_ctrl:1
	v_pk_mul_f32 v[44:45], v[8:9], v[40:41] op_sel_hi:[1,0]
	v_pk_mul_f32 v[46:47], v[10:11], v[40:41] op_sel_hi:[1,0]
	v_add_f32_dpp v48, v48, v48 quad_perm:[2,3,0,1] row_mask:0xf bank_mask:0xf bound_ctrl:1
	v_pk_fma_f32 v[44:45], v[94:95], v[4:5], v[44:45]
	v_pk_fma_f32 v[46:47], v[96:97], v[6:7], v[46:47]
	v_add_f32_dpp v48, v48, v48 row_half_mirror row_mask:0xf bank_mask:0xf bound_ctrl:1
	ds_read_b128 v[32:35], v50 offset:8960
	ds_read_b128 v[36:39], v50 offset:7680
	v_add_f32_dpp v48, v48, v48 row_mirror row_mask:0xf bank_mask:0xf bound_ctrl:1
	v_pk_fma_f32 v[44:45], v[12:13], v[48:49], v[44:45] op_sel_hi:[1,0,1]
	v_pk_fma_f32 v[46:47], v[14:15], v[48:49], v[46:47] op_sel_hi:[1,0,1]
	v_pk_mul_f32 v[48:49], v[44:45], v[20:21]
	v_pk_mul_f32 v[76:77], v[44:45], v[16:17]
	v_pk_fma_f32 v[48:49], v[46:47], v[22:23], v[48:49]
	v_pk_fma_f32 v[76:77], v[46:47], v[18:19], v[76:77]
	v_add_f32_e32 v48, v48, v49
	v_add_f32_e32 v64, v76, v77
	ds_read_b128 v[20:23], v50 offset:11776
	ds_read_b128 v[8:11], v50 offset:9728
	ds_read2st64_b32 v[42:43], v51 offset0:39 offset1:45
	ds_read_b128 v[4:7], v50 offset:9472
	s_waitcnt lgkmcnt(4)
	v_add_f32_dpp v48, v48, v48 quad_perm:[1,0,3,2] row_mask:0xf bank_mask:0xf bound_ctrl:1
	v_pk_mul_f32 v[94:95], v[28:29], v[40:41] op_sel:[0,1]
	v_pk_mul_f32 v[96:97], v[30:31], v[40:41] op_sel:[0,1]
	v_add_f32_dpp v48, v48, v48 quad_perm:[2,3,0,1] row_mask:0xf bank_mask:0xf bound_ctrl:1
	v_pk_fma_f32 v[94:95], v[44:45], v[24:25], v[94:95]
	v_pk_fma_f32 v[96:97], v[46:47], v[26:27], v[96:97]
	v_add_f32_dpp v48, v48, v48 row_half_mirror row_mask:0xf bank_mask:0xf bound_ctrl:1
	ds_read_b128 v[12:15], v50 offset:10496
	ds_read_b128 v[16:19], v50 offset:9216
	v_add_f32_dpp v48, v48, v48 row_mirror row_mask:0xf bank_mask:0xf bound_ctrl:1
	v_pk_fma_f32 v[94:95], v[32:33], v[48:49], v[94:95] op_sel_hi:[1,0,1]
	v_pk_fma_f32 v[96:97], v[34:35], v[48:49], v[96:97] op_sel_hi:[1,0,1]
	v_pk_mul_f32 v[48:49], v[94:95], v[0:1]
	v_pk_mul_f32 v[76:77], v[94:95], v[36:37]
	v_pk_fma_f32 v[48:49], v[96:97], v[2:3], v[48:49]
	v_pk_fma_f32 v[76:77], v[96:97], v[38:39], v[76:77]
	v_add_f32_e32 v48, v48, v49
	v_add_f32_e32 v65, v76, v77
	ds_read_b128 v[0:3], v50 offset:13312
	ds_read_b128 v[28:31], v50 offset:11264
	ds_read_b128 v[24:27], v50 offset:11008
	s_waitcnt lgkmcnt(3)
	v_add_f32_dpp v48, v48, v48 quad_perm:[1,0,3,2] row_mask:0xf bank_mask:0xf bound_ctrl:1
	v_pk_mul_f32 v[44:45], v[8:9], v[42:43] op_sel_hi:[1,0]
	v_pk_mul_f32 v[46:47], v[10:11], v[42:43] op_sel_hi:[1,0]
	v_add_f32_dpp v48, v48, v48 quad_perm:[2,3,0,1] row_mask:0xf bank_mask:0xf bound_ctrl:1
	v_pk_fma_f32 v[44:45], v[94:95], v[4:5], v[44:45]
	v_pk_fma_f32 v[46:47], v[96:97], v[6:7], v[46:47]
	v_add_f32_dpp v48, v48, v48 row_half_mirror row_mask:0xf bank_mask:0xf bound_ctrl:1
	ds_read_b128 v[32:35], v50 offset:12032
	ds_read_b128 v[36:39], v50 offset:10752
	v_add_f32_dpp v48, v48, v48 row_mirror row_mask:0xf bank_mask:0xf bound_ctrl:1
	v_pk_fma_f32 v[44:45], v[12:13], v[48:49], v[44:45] op_sel_hi:[1,0,1]
	v_pk_fma_f32 v[46:47], v[14:15], v[48:49], v[46:47] op_sel_hi:[1,0,1]
	v_pk_mul_f32 v[48:49], v[44:45], v[20:21]
	v_pk_mul_f32 v[76:77], v[44:45], v[16:17]
	v_pk_fma_f32 v[48:49], v[46:47], v[22:23], v[48:49]
	v_pk_fma_f32 v[76:77], v[46:47], v[18:19], v[76:77]
	v_add_f32_e32 v48, v48, v49
	v_add_f32_e32 v66, v76, v77
	ds_read_b128 v[20:23], v50 offset:14848
	ds_read_b128 v[8:11], v50 offset:12800
	ds_read2st64_b32 v[40:41], v51 offset0:51 offset1:57
	ds_read_b128 v[4:7], v50 offset:12544
	s_waitcnt lgkmcnt(4)
	v_add_f32_dpp v48, v48, v48 quad_perm:[1,0,3,2] row_mask:0xf bank_mask:0xf bound_ctrl:1
	v_pk_mul_f32 v[94:95], v[28:29], v[42:43] op_sel:[0,1]
	v_pk_mul_f32 v[96:97], v[30:31], v[42:43] op_sel:[0,1]
	v_add_f32_dpp v48, v48, v48 quad_perm:[2,3,0,1] row_mask:0xf bank_mask:0xf bound_ctrl:1
	v_pk_fma_f32 v[94:95], v[44:45], v[24:25], v[94:95]
	v_pk_fma_f32 v[96:97], v[46:47], v[26:27], v[96:97]
	v_add_f32_dpp v48, v48, v48 row_half_mirror row_mask:0xf bank_mask:0xf bound_ctrl:1
	ds_read_b128 v[12:15], v50 offset:13568
	ds_read_b128 v[16:19], v50 offset:12288
	v_add_f32_dpp v48, v48, v48 row_mirror row_mask:0xf bank_mask:0xf bound_ctrl:1
	v_pk_fma_f32 v[94:95], v[32:33], v[48:49], v[94:95] op_sel_hi:[1,0,1]
	v_pk_fma_f32 v[96:97], v[34:35], v[48:49], v[96:97] op_sel_hi:[1,0,1]
	v_pk_mul_f32 v[48:49], v[94:95], v[0:1]
	v_pk_mul_f32 v[76:77], v[94:95], v[36:37]
	v_pk_fma_f32 v[48:49], v[96:97], v[2:3], v[48:49]
	v_pk_fma_f32 v[76:77], v[96:97], v[38:39], v[76:77]
	v_add_f32_e32 v48, v48, v49
	v_add_f32_e32 v67, v76, v77
	ds_read_b128 v[0:3], v50 offset:16384
	ds_read_b128 v[28:31], v50 offset:14336
	ds_read_b128 v[24:27], v50 offset:14080
	s_waitcnt lgkmcnt(3)
	v_add_f32_dpp v48, v48, v48 quad_perm:[1,0,3,2] row_mask:0xf bank_mask:0xf bound_ctrl:1
	v_pk_mul_f32 v[44:45], v[8:9], v[40:41] op_sel_hi:[1,0]
	v_pk_mul_f32 v[46:47], v[10:11], v[40:41] op_sel_hi:[1,0]
	v_add_f32_dpp v48, v48, v48 quad_perm:[2,3,0,1] row_mask:0xf bank_mask:0xf bound_ctrl:1
	v_pk_fma_f32 v[44:45], v[94:95], v[4:5], v[44:45]
	v_pk_fma_f32 v[46:47], v[96:97], v[6:7], v[46:47]
	v_add_f32_dpp v48, v48, v48 row_half_mirror row_mask:0xf bank_mask:0xf bound_ctrl:1
	ds_read_b128 v[32:35], v50 offset:15104
	ds_read_b128 v[36:39], v50 offset:13824
	v_add_f32_dpp v48, v48, v48 row_mirror row_mask:0xf bank_mask:0xf bound_ctrl:1
	v_pk_fma_f32 v[44:45], v[12:13], v[48:49], v[44:45] op_sel_hi:[1,0,1]
	v_pk_fma_f32 v[46:47], v[14:15], v[48:49], v[46:47] op_sel_hi:[1,0,1]
	v_pk_mul_f32 v[48:49], v[44:45], v[20:21]
	v_pk_mul_f32 v[76:77], v[44:45], v[16:17]
	v_pk_fma_f32 v[48:49], v[46:47], v[22:23], v[48:49]
	v_pk_fma_f32 v[76:77], v[46:47], v[18:19], v[76:77]
	v_add_f32_e32 v48, v48, v49
	v_add_f32_e32 v68, v76, v77
	ds_read_b128 v[20:23], v50 offset:17920
	ds_read_b128 v[8:11], v50 offset:15872
	ds_read2st64_b32 v[42:43], v51 offset0:63 offset1:69
	ds_read_b128 v[4:7], v50 offset:15616
	s_waitcnt lgkmcnt(4)
; #define LAS __attribute__((address_space(3)))
; __device__ __forceinline__ float sum16(float x) { x += dpp_f<0xB1>(x); x += dpp_f<0x4E>(x); x += dpp_f<0x141>(x); x += dpp_f<0x140>(x); return x; }
; __device__ __forceinline__ void rwkv_scan_phase(LAS unsigned char* lds, const bf16_t* RKV, const float* DEC, const float* AF, const float* k_k, const float* k_a, const float* r_k, float* BON, float* Y, int bx, const int tid) {
;     ...
;             for (int t = 0; t < SC_T; ++t) {
;                 f32x4 r4n = r4, w4n = w4, k4n = k4, a4n = a4, b4n = b4; float vvn = vv;
;                 if (t + 1 < SC_T) { const LAS unsigned char* p = base + (t + 1) * SC_TOK;
;                     r4n = *(const LAS f32x4*)(p); w4n = *(const LAS f32x4*)(p + 256); k4n = *(const LAS f32x4*)(p + 512); a4n = *(const LAS f32x4*)(p + 1024); b4n = *(const LAS f32x4*)(p + 1280);
;                     vvn = *(const LAS float*)(vbase + (t + 1) * SC_TOK); }
;                 const f32x2 a01 = {a4[0], a4[1]}, a23 = {a4[2], a4[3]}, w01 = {w4[0], w4[1]}, w23 = {w4[2], w4[3]}, b01 = {b4[0], b4[1]}, b23 = {b4[2], b4[3]}, k01 = {k4[0], k4[1]}, k23 = {k4[2], k4[3]}, r01 = {r4[0], r4[1]}, r23 = {r4[2], r4[3]};
;                 const f32x2 tsa = S01 * a01 + S23 * a23; const float sa = sum16(tsa[0] + tsa[1]);
;                 S01 = S01 * w01 + (b01 * sa + k01 * vv); S23 = S23 * w23 + (b23 * sa + k23 * vv);
;                 const f32x2 ty = S01 * r01 + S23 * r23; const float y = sum16(ty[0] + ty[1]);
	v_add_f32_dpp v48, v48, v48 quad_perm:[1,0,3,2] row_mask:0xf bank_mask:0xf bound_ctrl:1
	v_pk_mul_f32 v[94:95], v[28:29], v[40:41] op_sel:[0,1]
	v_pk_mul_f32 v[96:97], v[30:31], v[40:41] op_sel:[0,1]
	v_add_f32_dpp v48, v48, v48 quad_perm:[2,3,0,1] row_mask:0xf bank_mask:0xf bound_ctrl:1
	v_pk_fma_f32 v[94:95], v[44:45], v[24:25], v[94:95]
	v_pk_fma_f32 v[96:97], v[46:47], v[26:27], v[96:97]
	v_add_f32_dpp v48, v48, v48 row_half_mirror row_mask:0xf bank_mask:0xf bound_ctrl:1
	ds_read_b128 v[12:15], v50 offset:16640
	ds_read_b128 v[16:19], v50 offset:15360
	v_add_f32_dpp v48, v48, v48 row_mirror row_mask:0xf bank_mask:0xf bound_ctrl:1
	v_pk_fma_f32 v[94:95], v[32:33], v[48:49], v[94:95] op_sel_hi:[1,0,1]
	v_pk_fma_f32 v[96:97], v[34:35], v[48:49], v[96:97] op_sel_hi:[1,0,1]
	v_pk_mul_f32 v[48:49], v[94:95], v[0:1]
	v_pk_mul_f32 v[76:77], v[94:95], v[36:37]
	v_pk_fma_f32 v[48:49], v[96:97], v[2:3], v[48:49]
	v_pk_fma_f32 v[76:77], v[96:97], v[38:39], v[76:77]
	v_add_f32_e32 v48, v48, v49
	v_add_f32_e32 v69, v76, v77
	ds_read_b128 v[0:3], v50 offset:19456
	ds_read_b128 v[28:31], v50 offset:17408
	ds_read_b128 v[24:27], v50 offset:17152
	s_waitcnt lgkmcnt(3)
	v_add_f32_dpp v48, v48, v48 quad_perm:[1,0,3,2] row_mask:0xf bank_mask:0xf bound_ctrl:1
	v_pk_mul_f32 v[44:45], v[8:9], v[42:43] op_sel_hi:[1,0]
	v_pk_mul_f32 v[46:47], v[10:11], v[42:43] op_sel_hi:[1,0]
	v_add_f32_dpp v48, v48, v48 quad_perm:[2,3,0,1] row_mask:0xf bank_mask:0xf bound_ctrl:1
	v_pk_fma_f32 v[44:45], v[94:95], v[4:5], v[44:45]
	v_pk_fma_f32 v[46:47], v[96:97], v[6:7], v[46:47]
	v_add_f32_dpp v48, v48, v48 row_half_mirror row_mask:0xf bank_mask:0xf bound_ctrl:1
	ds_read_b128 v[32:35], v50 offset:18176
	ds_read_b128 v[36:39], v50 offset:16896
	v_add_f32_dpp v48, v48, v48 row_mirror row_mask:0xf bank_mask:0xf bound_ctrl:1
	v_pk_fma_f32 v[44:45], v[12:13], v[48:49], v[44:45] op_sel_hi:[1,0,1]
	v_pk_fma_f32 v[46:47], v[14:15], v[48:49], v[46:47] op_sel_hi:[1,0,1]
	v_pk_mul_f32 v[48:49], v[44:45], v[20:21]
	v_pk_mul_f32 v[76:77], v[44:45], v[16:17]
	v_pk_fma_f32 v[48:49], v[46:47], v[22:23], v[48:49]
	v_pk_fma_f32 v[76:77], v[46:47], v[18:19], v[76:77]
	v_add_f32_e32 v48, v48, v49
	v_add_f32_e32 v70, v76, v77
	ds_read_b128 v[20:23], v50 offset:20992
	ds_read_b128 v[8:11], v50 offset:18944
	ds_read2st64_b32 v[40:41], v51 offset0:75 offset1:81
	ds_read_b128 v[4:7], v50 offset:18688
	s_waitcnt lgkmcnt(4)
	v_add_f32_dpp v48, v48, v48 quad_perm:[1,0,3,2] row_mask:0xf bank_mask:0xf bound_ctrl:1
	v_pk_mul_f32 v[94:95], v[28:29], v[42:43] op_sel:[0,1]
	v_pk_mul_f32 v[96:97], v[30:31], v[42:43] op_sel:[0,1]
	v_add_f32_dpp v48, v48, v48 quad_perm:[2,3,0,1] row_mask:0xf bank_mask:0xf bound_ctrl:1
	v_pk_fma_f32 v[94:95], v[44:45], v[24:25], v[94:95]
	v_pk_fma_f32 v[96:97], v[46:47], v[26:27], v[96:97]
	v_add_f32_dpp v48, v48, v48 row_half_mirror row_mask:0xf bank_mask:0xf bound_ctrl:1
	ds_read_b128 v[12:15], v50 offset:19712
	ds_read_b128 v[16:19], v50 offset:18432
	v_add_f32_dpp v48, v48, v48 row_mirror row_mask:0xf bank_mask:0xf bound_ctrl:1
	v_pk_fma_f32 v[94:95], v[32:33], v[48:49], v[94:95] op_sel_hi:[1,0,1]
	v_pk_fma_f32 v[96:97], v[34:35], v[48:49], v[96:97] op_sel_hi:[1,0,1]
	v_pk_mul_f32 v[48:49], v[94:95], v[0:1]
	v_pk_mul_f32 v[76:77], v[94:95], v[36:37]
	v_pk_fma_f32 v[48:49], v[96:97], v[2:3], v[48:49]
	v_pk_fma_f32 v[76:77], v[96:97], v[38:39], v[76:77]
	v_add_f32_e32 v48, v48, v49
	v_add_f32_e32 v71, v76, v77
	ds_read_b128 v[0:3], v50 offset:22528
	ds_read_b128 v[28:31], v50 offset:20480
	ds_read_b128 v[24:27], v50 offset:20224
	s_waitcnt lgkmcnt(3)
	v_add_f32_dpp v48, v48, v48 quad_perm:[1,0,3,2] row_mask:0xf bank_mask:0xf bound_ctrl:1
	v_pk_mul_f32 v[44:45], v[8:9], v[40:41] op_sel_hi:[1,0]
	v_pk_mul_f32 v[46:47], v[10:11], v[40:41] op_sel_hi:[1,0]
	v_add_f32_dpp v48, v48, v48 quad_perm:[2,3,0,1] row_mask:0xf bank_mask:0xf bound_ctrl:1
	v_pk_fma_f32 v[44:45], v[94:95], v[4:5], v[44:45]
	v_pk_fma_f32 v[46:47], v[96:97], v[6:7], v[46:47]
	v_add_f32_dpp v48, v48, v48 row_half_mirror row_mask:0xf bank_mask:0xf bound_ctrl:1
	ds_read_b128 v[32:35], v50 offset:21248
	ds_read_b128 v[36:39], v50 offset:19968
	v_add_f32_dpp v48, v48, v48 row_mirror row_mask:0xf bank_mask:0xf bound_ctrl:1
	v_pk_fma_f32 v[44:45], v[12:13], v[48:49], v[44:45] op_sel_hi:[1,0,1]
	v_pk_fma_f32 v[46:47], v[14:15], v[48:49], v[46:47] op_sel_hi:[1,0,1]
	v_pk_mul_f32 v[48:49], v[44:45], v[20:21]
	v_pk_mul_f32 v[76:77], v[44:45], v[16:17]
	v_pk_fma_f32 v[48:49], v[46:47], v[22:23], v[48:49]
	v_pk_fma_f32 v[76:77], v[46:47], v[18:19], v[76:77]
	v_add_f32_e32 v48, v48, v49
	v_add_f32_e32 v72, v76, v77
	ds_read_b128 v[20:23], v50 offset:24064
	ds_read_b128 v[8:11], v50 offset:22016
	ds_read2st64_b32 v[42:43], v51 offset0:87 offset1:93
	ds_read_b128 v[4:7], v50 offset:21760
	s_waitcnt lgkmcnt(4)
	v_add_f32_dpp v48, v48, v48 quad_perm:[1,0,3,2] row_mask:0xf bank_mask:0xf bound_ctrl:1
	v_pk_mul_f32 v[94:95], v[28:29], v[40:41] op_sel:[0,1]
	v_pk_mul_f32 v[96:97], v[30:31], v[40:41] op_sel:[0,1]
	v_add_f32_dpp v48, v48, v48 quad_perm:[2,3,0,1] row_mask:0xf bank_mask:0xf bound_ctrl:1
	v_pk_fma_f32 v[94:95], v[44:45], v[24:25], v[94:95]
	v_pk_fma_f32 v[96:97], v[46:47], v[26:27], v[96:97]
	v_add_f32_dpp v48, v48, v48 row_half_mirror row_mask:0xf bank_mask:0xf bound_ctrl:1
	ds_read_b128 v[12:15], v50 offset:22784
	ds_read_b128 v[16:19], v50 offset:21504
	v_add_f32_dpp v48, v48, v48 row_mirror row_mask:0xf bank_mask:0xf bound_ctrl:1
	v_pk_fma_f32 v[94:95], v[32:33], v[48:49], v[94:95] op_sel_hi:[1,0,1]
	v_pk_fma_f32 v[96:97], v[34:35], v[48:49], v[96:97] op_sel_hi:[1,0,1]
	v_pk_mul_f32 v[48:49], v[94:95], v[0:1]
	v_pk_mul_f32 v[76:77], v[94:95], v[36:37]
	v_pk_fma_f32 v[48:49], v[96:97], v[2:3], v[48:49]
	v_pk_fma_f32 v[76:77], v[96:97], v[38:39], v[76:77]
	v_add_f32_e32 v48, v48, v49
	v_add_f32_e32 v73, v76, v77
	ds_read_b128 v[0:3], v50 offset:25600
	ds_read_b128 v[28:31], v50 offset:23552
	ds_read_b128 v[24:27], v50 offset:23296
	s_waitcnt lgkmcnt(3)
; __device__ __forceinline__ float sum16(float x) { x += dpp_f<0xB1>(x); x += dpp_f<0x4E>(x); x += dpp_f<0x141>(x); x += dpp_f<0x140>(x); return x; }
; __device__ __forceinline__ void rwkv_scan_phase(LAS unsigned char* lds, const bf16_t* RKV, const float* DEC, const float* AF, const float* k_k, const float* k_a, const float* r_k, float* BON, float* Y, int bx, const int tid) {
;     ...
;                 const f32x2 tsa = S01 * a01 + S23 * a23; const float sa = sum16(tsa[0] + tsa[1]);
;                 S01 = S01 * w01 + (b01 * sa + k01 * vv); S23 = S23 * w23 + (b23 * sa + k23 * vv);
;                 const f32x2 ty = S01 * r01 + S23 * r23; const float y = sum16(ty[0] + ty[1]);
;                 ykeep = ((lane & 15) == (t & 15)) ? y : ykeep;
;                 if ((t & 15) == 15) yp[(size_t)(c * SC_T + (t - 15) + (lane & 15)) * 2048] = ykeep;
	v_add_f32_dpp v48, v48, v48 quad_perm:[1,0,3,2] row_mask:0xf bank_mask:0xf bound_ctrl:1
	v_pk_mul_f32 v[44:45], v[8:9], v[42:43] op_sel_hi:[1,0]
	v_pk_mul_f32 v[46:47], v[10:11], v[42:43] op_sel_hi:[1,0]
	v_add_f32_dpp v48, v48, v48 quad_perm:[2,3,0,1] row_mask:0xf bank_mask:0xf bound_ctrl:1
	v_pk_fma_f32 v[44:45], v[94:95], v[4:5], v[44:45]
	v_pk_fma_f32 v[46:47], v[96:97], v[6:7], v[46:47]
	v_add_f32_dpp v48, v48, v48 row_half_mirror row_mask:0xf bank_mask:0xf bound_ctrl:1
	ds_read_b128 v[32:35], v50 offset:24320
	ds_read_b128 v[36:39], v50 offset:23040
	v_add_f32_dpp v48, v48, v48 row_mirror row_mask:0xf bank_mask:0xf bound_ctrl:1
	v_pk_fma_f32 v[44:45], v[12:13], v[48:49], v[44:45] op_sel_hi:[1,0,1]
	v_pk_fma_f32 v[46:47], v[14:15], v[48:49], v[46:47] op_sel_hi:[1,0,1]
	v_pk_mul_f32 v[48:49], v[44:45], v[20:21]
	v_pk_mul_f32 v[76:77], v[44:45], v[16:17]
	v_pk_fma_f32 v[48:49], v[46:47], v[22:23], v[48:49]
	v_pk_fma_f32 v[76:77], v[46:47], v[18:19], v[76:77]
	v_add_f32_e32 v48, v48, v49
	v_add_f32_e32 v74, v76, v77
	ds_read_b128 v[20:23], v50 offset:27136
	ds_read_b128 v[8:11], v50 offset:25088
	ds_read2st64_b32 v[40:41], v51 offset0:99 offset1:105
	ds_read_b128 v[4:7], v50 offset:24832
	s_waitcnt lgkmcnt(4)
	v_add_f32_dpp v48, v48, v48 quad_perm:[1,0,3,2] row_mask:0xf bank_mask:0xf bound_ctrl:1
	v_pk_mul_f32 v[94:95], v[28:29], v[42:43] op_sel:[0,1]
	v_pk_mul_f32 v[96:97], v[30:31], v[42:43] op_sel:[0,1]
	v_add_f32_dpp v48, v48, v48 quad_perm:[2,3,0,1] row_mask:0xf bank_mask:0xf bound_ctrl:1
	v_pk_fma_f32 v[94:95], v[44:45], v[24:25], v[94:95]
	v_pk_fma_f32 v[96:97], v[46:47], v[26:27], v[96:97]
	v_add_f32_dpp v48, v48, v48 row_half_mirror row_mask:0xf bank_mask:0xf bound_ctrl:1
	ds_read_b128 v[12:15], v50 offset:25856
	ds_read_b128 v[16:19], v50 offset:24576
	v_add_f32_dpp v48, v48, v48 row_mirror row_mask:0xf bank_mask:0xf bound_ctrl:1
	v_pk_fma_f32 v[94:95], v[32:33], v[48:49], v[94:95] op_sel_hi:[1,0,1]
	v_pk_fma_f32 v[96:97], v[34:35], v[48:49], v[96:97] op_sel_hi:[1,0,1]
	v_pk_mul_f32 v[48:49], v[94:95], v[0:1]
	v_pk_mul_f32 v[76:77], v[94:95], v[36:37]
	v_pk_fma_f32 v[48:49], v[96:97], v[2:3], v[48:49]
	v_pk_fma_f32 v[76:77], v[96:97], v[38:39], v[76:77]
	v_add_f32_e32 v48, v48, v49
	v_add_f32_e32 v75, v76, v77
	v_add_f32_dpp v60, v60, v60 row_mirror row_mask:0xf bank_mask:0x3 bound_ctrl:1
	v_add_f32_dpp v60, v68, v68 row_mirror row_mask:0xf bank_mask:0xc bound_ctrl:1
	v_add_f32_dpp v61, v61, v61 row_mirror row_mask:0xf bank_mask:0x3 bound_ctrl:1
	v_add_f32_dpp v61, v69, v69 row_mirror row_mask:0xf bank_mask:0xc bound_ctrl:1
	v_add_f32_dpp v62, v62, v62 row_mirror row_mask:0xf bank_mask:0x3 bound_ctrl:1
	v_add_f32_dpp v62, v70, v70 row_mirror row_mask:0xf bank_mask:0xc bound_ctrl:1
	v_add_f32_dpp v63, v63, v63 row_mirror row_mask:0xf bank_mask:0x3 bound_ctrl:1
	v_add_f32_dpp v63, v71, v71 row_mirror row_mask:0xf bank_mask:0xc bound_ctrl:1
	v_add_f32_dpp v64, v64, v64 row_mirror row_mask:0xf bank_mask:0x3 bound_ctrl:1
	v_add_f32_dpp v64, v72, v72 row_mirror row_mask:0xf bank_mask:0xc bound_ctrl:1
	v_add_f32_dpp v65, v65, v65 row_mirror row_mask:0xf bank_mask:0x3 bound_ctrl:1
	v_add_f32_dpp v65, v73, v73 row_mirror row_mask:0xf bank_mask:0xc bound_ctrl:1
	v_add_f32_dpp v66, v66, v66 row_mirror row_mask:0xf bank_mask:0x3 bound_ctrl:1
	v_add_f32_dpp v66, v74, v74 row_mirror row_mask:0xf bank_mask:0xc bound_ctrl:1
	v_add_f32_dpp v67, v67, v67 row_mirror row_mask:0xf bank_mask:0x3 bound_ctrl:1
	v_add_f32_dpp v67, v75, v75 row_mirror row_mask:0xf bank_mask:0xc bound_ctrl:1
	v_add_f32_dpp v60, v60, v60 row_half_mirror row_mask:0xf bank_mask:0x5 bound_ctrl:1
	v_add_f32_dpp v60, v64, v64 row_half_mirror row_mask:0xf bank_mask:0xa bound_ctrl:1
	v_add_f32_dpp v61, v61, v61 row_half_mirror row_mask:0xf bank_mask:0x5 bound_ctrl:1
	v_add_f32_dpp v61, v65, v65 row_half_mirror row_mask:0xf bank_mask:0xa bound_ctrl:1
	v_add_f32_dpp v62, v62, v62 row_half_mirror row_mask:0xf bank_mask:0x5 bound_ctrl:1
	v_add_f32_dpp v62, v66, v66 row_half_mirror row_mask:0xf bank_mask:0xa bound_ctrl:1
	v_add_f32_dpp v63, v63, v63 row_half_mirror row_mask:0xf bank_mask:0x5 bound_ctrl:1
	v_add_f32_dpp v63, v67, v67 row_half_mirror row_mask:0xf bank_mask:0xa bound_ctrl:1
	v_cndmask_b32_e64 v76, v62, v60, s[46:47]
	v_cndmask_b32_e64 v77, v63, v61, s[46:47]
	v_cndmask_b32_e64 v78, v60, v62, s[46:47]
	v_cndmask_b32_e64 v79, v61, v63, s[46:47]
	s_nop 0
	v_add_f32_dpp v60, v76, v78 quad_perm:[2,3,0,1] row_mask:0xf bank_mask:0xf bound_ctrl:1
	v_add_f32_dpp v61, v77, v79 quad_perm:[2,3,0,1] row_mask:0xf bank_mask:0xf bound_ctrl:1
	v_cndmask_b32_e64 v76, v61, v60, s[40:41]
	v_cndmask_b32_e64 v78, v60, v61, s[40:41]
	s_nop 1
	v_add_f32_dpp v60, v76, v78 quad_perm:[1,0,3,2] row_mask:0xf bank_mask:0xf bound_ctrl:1
	global_store_dword v[92:93], v60, off
	ds_read_b128 v[0:3], v50 offset:28672
	ds_read_b128 v[28:31], v50 offset:26624
	ds_read_b128 v[24:27], v50 offset:26368
	s_waitcnt lgkmcnt(3)
	v_add_f32_dpp v48, v48, v48 quad_perm:[1,0,3,2] row_mask:0xf bank_mask:0xf bound_ctrl:1
	v_pk_mul_f32 v[44:45], v[8:9], v[40:41] op_sel_hi:[1,0]
	v_pk_mul_f32 v[46:47], v[10:11], v[40:41] op_sel_hi:[1,0]
	v_add_f32_dpp v48, v48, v48 quad_perm:[2,3,0,1] row_mask:0xf bank_mask:0xf bound_ctrl:1
	v_pk_fma_f32 v[44:45], v[94:95], v[4:5], v[44:45]
	v_pk_fma_f32 v[46:47], v[96:97], v[6:7], v[46:47]
	v_add_f32_dpp v48, v48, v48 row_half_mirror row_mask:0xf bank_mask:0xf bound_ctrl:1
	ds_read_b128 v[32:35], v50 offset:27392
	ds_read_b128 v[36:39], v50 offset:26112
	v_add_f32_dpp v48, v48, v48 row_mirror row_mask:0xf bank_mask:0xf bound_ctrl:1
	v_pk_fma_f32 v[44:45], v[12:13], v[48:49], v[44:45] op_sel_hi:[1,0,1]
	v_pk_fma_f32 v[46:47], v[14:15], v[48:49], v[46:47] op_sel_hi:[1,0,1]
	v_pk_mul_f32 v[48:49], v[44:45], v[20:21]
	v_pk_mul_f32 v[76:77], v[44:45], v[16:17]
	v_pk_fma_f32 v[48:49], v[46:47], v[22:23], v[48:49]
	v_pk_fma_f32 v[76:77], v[46:47], v[18:19], v[76:77]
	v_add_f32_e32 v48, v48, v49
	v_add_f32_e32 v60, v76, v77
	ds_read_b128 v[20:23], v50 offset:30208
	ds_read_b128 v[8:11], v50 offset:28160
	ds_read2st64_b32 v[42:43], v51 offset0:111 offset1:117
	ds_read_b128 v[4:7], v50 offset:27904
	s_waitcnt lgkmcnt(4)
; #define LAS __attribute__((address_space(3)))
; __device__ __forceinline__ float sum16(float x) { x += dpp_f<0xB1>(x); x += dpp_f<0x4E>(x); x += dpp_f<0x141>(x); x += dpp_f<0x140>(x); return x; }
; __device__ __forceinline__ void rwkv_scan_phase(LAS unsigned char* lds, const bf16_t* RKV, const float* DEC, const float* AF, const float* k_k, const float* k_a, const float* r_k, float* BON, float* Y, int bx, const int tid) {
;     ...
;             for (int t = 0; t < SC_T; ++t) {
;                 f32x4 r4n = r4, w4n = w4, k4n = k4, a4n = a4, b4n = b4; float vvn = vv;
;                 if (t + 1 < SC_T) { const LAS unsigned char* p = base + (t + 1) * SC_TOK;
;                     r4n = *(const LAS f32x4*)(p); w4n = *(const LAS f32x4*)(p + 256); k4n = *(const LAS f32x4*)(p + 512); a4n = *(const LAS f32x4*)(p + 1024); b4n = *(const LAS f32x4*)(p + 1280);
;                     vvn = *(const LAS float*)(vbase + (t + 1) * SC_TOK); }
;                 const f32x2 a01 = {a4[0], a4[1]}, a23 = {a4[2], a4[3]}, w01 = {w4[0], w4[1]}, w23 = {w4[2], w4[3]}, b01 = {b4[0], b4[1]}, b23 = {b4[2], b4[3]}, k01 = {k4[0], k4[1]}, k23 = {k4[2], k4[3]}, r01 = {r4[0], r4[1]}, r23 = {r4[2], r4[3]};
;                 const f32x2 tsa = S01 * a01 + S23 * a23; const float sa = sum16(tsa[0] + tsa[1]);
;                 S01 = S01 * w01 + (b01 * sa + k01 * vv); S23 = S23 * w23 + (b23 * sa + k23 * vv);
;                 const f32x2 ty = S01 * r01 + S23 * r23; const float y = sum16(ty[0] + ty[1]);
	v_add_f32_dpp v48, v48, v48 quad_perm:[1,0,3,2] row_mask:0xf bank_mask:0xf bound_ctrl:1
	v_pk_mul_f32 v[94:95], v[28:29], v[40:41] op_sel:[0,1]
	v_pk_mul_f32 v[96:97], v[30:31], v[40:41] op_sel:[0,1]
	v_add_f32_dpp v48, v48, v48 quad_perm:[2,3,0,1] row_mask:0xf bank_mask:0xf bound_ctrl:1
	v_pk_fma_f32 v[94:95], v[44:45], v[24:25], v[94:95]
	v_pk_fma_f32 v[96:97], v[46:47], v[26:27], v[96:97]
	v_add_f32_dpp v48, v48, v48 row_half_mirror row_mask:0xf bank_mask:0xf bound_ctrl:1
	ds_read_b128 v[12:15], v50 offset:28928
	ds_read_b128 v[16:19], v50 offset:27648
	v_add_f32_dpp v48, v48, v48 row_mirror row_mask:0xf bank_mask:0xf bound_ctrl:1
	v_pk_fma_f32 v[94:95], v[32:33], v[48:49], v[94:95] op_sel_hi:[1,0,1]
	v_pk_fma_f32 v[96:97], v[34:35], v[48:49], v[96:97] op_sel_hi:[1,0,1]
	v_pk_mul_f32 v[48:49], v[94:95], v[0:1]
	v_pk_mul_f32 v[76:77], v[94:95], v[36:37]
	v_pk_fma_f32 v[48:49], v[96:97], v[2:3], v[48:49]
	v_pk_fma_f32 v[76:77], v[96:97], v[38:39], v[76:77]
	v_add_f32_e32 v48, v48, v49
	v_add_f32_e32 v61, v76, v77
	ds_read_b128 v[0:3], v50 offset:31744
	ds_read_b128 v[28:31], v50 offset:29696
	ds_read_b128 v[24:27], v50 offset:29440
	s_waitcnt lgkmcnt(3)
	v_add_f32_dpp v48, v48, v48 quad_perm:[1,0,3,2] row_mask:0xf bank_mask:0xf bound_ctrl:1
	v_pk_mul_f32 v[44:45], v[8:9], v[42:43] op_sel_hi:[1,0]
	v_pk_mul_f32 v[46:47], v[10:11], v[42:43] op_sel_hi:[1,0]
	v_add_f32_dpp v48, v48, v48 quad_perm:[2,3,0,1] row_mask:0xf bank_mask:0xf bound_ctrl:1
	v_pk_fma_f32 v[44:45], v[94:95], v[4:5], v[44:45]
	v_pk_fma_f32 v[46:47], v[96:97], v[6:7], v[46:47]
	v_add_f32_dpp v48, v48, v48 row_half_mirror row_mask:0xf bank_mask:0xf bound_ctrl:1
	ds_read_b128 v[32:35], v50 offset:30464
	ds_read_b128 v[36:39], v50 offset:29184
	v_add_f32_dpp v48, v48, v48 row_mirror row_mask:0xf bank_mask:0xf bound_ctrl:1
	v_pk_fma_f32 v[44:45], v[12:13], v[48:49], v[44:45] op_sel_hi:[1,0,1]
	v_pk_fma_f32 v[46:47], v[14:15], v[48:49], v[46:47] op_sel_hi:[1,0,1]
	v_pk_mul_f32 v[48:49], v[44:45], v[20:21]
	v_pk_mul_f32 v[76:77], v[44:45], v[16:17]
	v_pk_fma_f32 v[48:49], v[46:47], v[22:23], v[48:49]
	v_pk_fma_f32 v[76:77], v[46:47], v[18:19], v[76:77]
	v_add_f32_e32 v48, v48, v49
	v_add_f32_e32 v62, v76, v77
	ds_read_b128 v[20:23], v50 offset:33280
	ds_read_b128 v[8:11], v50 offset:31232
	ds_read2st64_b32 v[40:41], v51 offset0:123 offset1:129
	ds_read_b128 v[4:7], v50 offset:30976
	s_waitcnt lgkmcnt(4)
	v_add_f32_dpp v48, v48, v48 quad_perm:[1,0,3,2] row_mask:0xf bank_mask:0xf bound_ctrl:1
	v_pk_mul_f32 v[94:95], v[28:29], v[42:43] op_sel:[0,1]
	v_pk_mul_f32 v[96:97], v[30:31], v[42:43] op_sel:[0,1]
	v_add_f32_dpp v48, v48, v48 quad_perm:[2,3,0,1] row_mask:0xf bank_mask:0xf bound_ctrl:1
	v_pk_fma_f32 v[94:95], v[44:45], v[24:25], v[94:95]
	v_pk_fma_f32 v[96:97], v[46:47], v[26:27], v[96:97]
	v_add_f32_dpp v48, v48, v48 row_half_mirror row_mask:0xf bank_mask:0xf bound_ctrl:1
	ds_read_b128 v[12:15], v50 offset:32000
	ds_read_b128 v[16:19], v50 offset:30720
	v_add_f32_dpp v48, v48, v48 row_mirror row_mask:0xf bank_mask:0xf bound_ctrl:1
	v_pk_fma_f32 v[94:95], v[32:33], v[48:49], v[94:95] op_sel_hi:[1,0,1]
	v_pk_fma_f32 v[96:97], v[34:35], v[48:49], v[96:97] op_sel_hi:[1,0,1]
	v_pk_mul_f32 v[48:49], v[94:95], v[0:1]
	v_pk_mul_f32 v[76:77], v[94:95], v[36:37]
	v_pk_fma_f32 v[48:49], v[96:97], v[2:3], v[48:49]
	v_pk_fma_f32 v[76:77], v[96:97], v[38:39], v[76:77]
	v_add_f32_e32 v48, v48, v49
	v_add_f32_e32 v63, v76, v77
	ds_read_b128 v[0:3], v50 offset:34816
	ds_read_b128 v[28:31], v50 offset:32768
	ds_read_b128 v[24:27], v50 offset:32512
	s_waitcnt lgkmcnt(3)
	v_add_f32_dpp v48, v48, v48 quad_perm:[1,0,3,2] row_mask:0xf bank_mask:0xf bound_ctrl:1
	v_pk_mul_f32 v[44:45], v[8:9], v[40:41] op_sel_hi:[1,0]
	v_pk_mul_f32 v[46:47], v[10:11], v[40:41] op_sel_hi:[1,0]
	v_add_f32_dpp v48, v48, v48 quad_perm:[2,3,0,1] row_mask:0xf bank_mask:0xf bound_ctrl:1
	v_pk_fma_f32 v[44:45], v[94:95], v[4:5], v[44:45]
	v_pk_fma_f32 v[46:47], v[96:97], v[6:7], v[46:47]
	v_add_f32_dpp v48, v48, v48 row_half_mirror row_mask:0xf bank_mask:0xf bound_ctrl:1
	ds_read_b128 v[32:35], v50 offset:33536
	ds_read_b128 v[36:39], v50 offset:32256
	v_add_f32_dpp v48, v48, v48 row_mirror row_mask:0xf bank_mask:0xf bound_ctrl:1
	v_pk_fma_f32 v[44:45], v[12:13], v[48:49], v[44:45] op_sel_hi:[1,0,1]
	v_pk_fma_f32 v[46:47], v[14:15], v[48:49], v[46:47] op_sel_hi:[1,0,1]
	v_pk_mul_f32 v[48:49], v[44:45], v[20:21]
	v_pk_mul_f32 v[76:77], v[44:45], v[16:17]
	v_pk_fma_f32 v[48:49], v[46:47], v[22:23], v[48:49]
	v_pk_fma_f32 v[76:77], v[46:47], v[18:19], v[76:77]
	v_add_f32_e32 v48, v48, v49
	v_add_f32_e32 v64, v76, v77
	ds_read_b128 v[20:23], v50 offset:36352
	ds_read_b128 v[8:11], v50 offset:34304
	ds_read2st64_b32 v[42:43], v51 offset0:135 offset1:141
	ds_read_b128 v[4:7], v50 offset:34048
	s_waitcnt lgkmcnt(4)
	v_add_f32_dpp v48, v48, v48 quad_perm:[1,0,3,2] row_mask:0xf bank_mask:0xf bound_ctrl:1
	v_pk_mul_f32 v[94:95], v[28:29], v[40:41] op_sel:[0,1]
	v_pk_mul_f32 v[96:97], v[30:31], v[40:41] op_sel:[0,1]
	v_add_f32_dpp v48, v48, v48 quad_perm:[2,3,0,1] row_mask:0xf bank_mask:0xf bound_ctrl:1
	v_pk_fma_f32 v[94:95], v[44:45], v[24:25], v[94:95]
	v_pk_fma_f32 v[96:97], v[46:47], v[26:27], v[96:97]
	v_add_f32_dpp v48, v48, v48 row_half_mirror row_mask:0xf bank_mask:0xf bound_ctrl:1
	ds_read_b128 v[12:15], v50 offset:35072
	ds_read_b128 v[16:19], v50 offset:33792
	v_add_f32_dpp v48, v48, v48 row_mirror row_mask:0xf bank_mask:0xf bound_ctrl:1
	v_pk_fma_f32 v[94:95], v[32:33], v[48:49], v[94:95] op_sel_hi:[1,0,1]
	v_pk_fma_f32 v[96:97], v[34:35], v[48:49], v[96:97] op_sel_hi:[1,0,1]
	v_pk_mul_f32 v[48:49], v[94:95], v[0:1]
	v_pk_mul_f32 v[76:77], v[94:95], v[36:37]
	v_pk_fma_f32 v[48:49], v[96:97], v[2:3], v[48:49]
	v_pk_fma_f32 v[76:77], v[96:97], v[38:39], v[76:77]
	v_add_f32_e32 v48, v48, v49
	v_add_f32_e32 v65, v76, v77
	ds_read_b128 v[0:3], v50 offset:37888
	ds_read_b128 v[28:31], v50 offset:35840
	ds_read_b128 v[24:27], v50 offset:35584
	s_waitcnt lgkmcnt(3)
; #define LAS __attribute__((address_space(3)))
; __device__ __forceinline__ float sum16(float x) { x += dpp_f<0xB1>(x); x += dpp_f<0x4E>(x); x += dpp_f<0x141>(x); x += dpp_f<0x140>(x); return x; }
; __device__ __forceinline__ void rwkv_scan_phase(LAS unsigned char* lds, const bf16_t* RKV, const float* DEC, const float* AF, const float* k_k, const float* k_a, const float* r_k, float* BON, float* Y, int bx, const int tid) {
;     ...
;             for (int t = 0; t < SC_T; ++t) {
;                 f32x4 r4n = r4, w4n = w4, k4n = k4, a4n = a4, b4n = b4; float vvn = vv;
;                 if (t + 1 < SC_T) { const LAS unsigned char* p = base + (t + 1) * SC_TOK;
;                     r4n = *(const LAS f32x4*)(p); w4n = *(const LAS f32x4*)(p + 256); k4n = *(const LAS f32x4*)(p + 512); a4n = *(const LAS f32x4*)(p + 1024); b4n = *(const LAS f32x4*)(p + 1280);
;                     vvn = *(const LAS float*)(vbase + (t + 1) * SC_TOK); }
;                 const f32x2 a01 = {a4[0], a4[1]}, a23 = {a4[2], a4[3]}, w01 = {w4[0], w4[1]}, w23 = {w4[2], w4[3]}, b01 = {b4[0], b4[1]}, b23 = {b4[2], b4[3]}, k01 = {k4[0], k4[1]}, k23 = {k4[2], k4[3]}, r01 = {r4[0], r4[1]}, r23 = {r4[2], r4[3]};
;                 const f32x2 tsa = S01 * a01 + S23 * a23; const float sa = sum16(tsa[0] + tsa[1]);
;                 S01 = S01 * w01 + (b01 * sa + k01 * vv); S23 = S23 * w23 + (b23 * sa + k23 * vv);
;                 const f32x2 ty = S01 * r01 + S23 * r23; const float y = sum16(ty[0] + ty[1]);
	v_add_f32_dpp v48, v48, v48 quad_perm:[1,0,3,2] row_mask:0xf bank_mask:0xf bound_ctrl:1
	v_pk_mul_f32 v[44:45], v[8:9], v[42:43] op_sel_hi:[1,0]
	v_pk_mul_f32 v[46:47], v[10:11], v[42:43] op_sel_hi:[1,0]
	v_add_f32_dpp v48, v48, v48 quad_perm:[2,3,0,1] row_mask:0xf bank_mask:0xf bound_ctrl:1
	v_pk_fma_f32 v[44:45], v[94:95], v[4:5], v[44:45]
	v_pk_fma_f32 v[46:47], v[96:97], v[6:7], v[46:47]
	v_add_f32_dpp v48, v48, v48 row_half_mirror row_mask:0xf bank_mask:0xf bound_ctrl:1
	ds_read_b128 v[32:35], v50 offset:36608
	ds_read_b128 v[36:39], v50 offset:35328
	v_add_f32_dpp v48, v48, v48 row_mirror row_mask:0xf bank_mask:0xf bound_ctrl:1
	v_pk_fma_f32 v[44:45], v[12:13], v[48:49], v[44:45] op_sel_hi:[1,0,1]
	v_pk_fma_f32 v[46:47], v[14:15], v[48:49], v[46:47] op_sel_hi:[1,0,1]
	v_pk_mul_f32 v[48:49], v[44:45], v[20:21]
	v_pk_mul_f32 v[76:77], v[44:45], v[16:17]
	v_pk_fma_f32 v[48:49], v[46:47], v[22:23], v[48:49]
	v_pk_fma_f32 v[76:77], v[46:47], v[18:19], v[76:77]
	v_add_f32_e32 v48, v48, v49
	v_add_f32_e32 v66, v76, v77
	ds_read_b128 v[20:23], v50 offset:39424
	ds_read_b128 v[8:11], v50 offset:37376
	ds_read2st64_b32 v[40:41], v51 offset0:147 offset1:153
	ds_read_b128 v[4:7], v50 offset:37120
	s_waitcnt lgkmcnt(4)
	v_add_f32_dpp v48, v48, v48 quad_perm:[1,0,3,2] row_mask:0xf bank_mask:0xf bound_ctrl:1
	v_pk_mul_f32 v[94:95], v[28:29], v[42:43] op_sel:[0,1]
	v_pk_mul_f32 v[96:97], v[30:31], v[42:43] op_sel:[0,1]
	v_add_f32_dpp v48, v48, v48 quad_perm:[2,3,0,1] row_mask:0xf bank_mask:0xf bound_ctrl:1
	v_pk_fma_f32 v[94:95], v[44:45], v[24:25], v[94:95]
	v_pk_fma_f32 v[96:97], v[46:47], v[26:27], v[96:97]
	v_add_f32_dpp v48, v48, v48 row_half_mirror row_mask:0xf bank_mask:0xf bound_ctrl:1
	ds_read_b128 v[12:15], v50 offset:38144
	ds_read_b128 v[16:19], v50 offset:36864
	v_add_f32_dpp v48, v48, v48 row_mirror row_mask:0xf bank_mask:0xf bound_ctrl:1
	v_pk_fma_f32 v[94:95], v[32:33], v[48:49], v[94:95] op_sel_hi:[1,0,1]
	v_pk_fma_f32 v[96:97], v[34:35], v[48:49], v[96:97] op_sel_hi:[1,0,1]
	v_pk_mul_f32 v[48:49], v[94:95], v[0:1]
	v_pk_mul_f32 v[76:77], v[94:95], v[36:37]
	v_pk_fma_f32 v[48:49], v[96:97], v[2:3], v[48:49]
	v_pk_fma_f32 v[76:77], v[96:97], v[38:39], v[76:77]
	v_add_f32_e32 v48, v48, v49
	v_add_f32_e32 v67, v76, v77
	ds_read_b128 v[0:3], v50 offset:40960
	ds_read_b128 v[28:31], v50 offset:38912
	ds_read_b128 v[24:27], v50 offset:38656
	s_waitcnt lgkmcnt(3)
	v_add_f32_dpp v48, v48, v48 quad_perm:[1,0,3,2] row_mask:0xf bank_mask:0xf bound_ctrl:1
	v_pk_mul_f32 v[44:45], v[8:9], v[40:41] op_sel_hi:[1,0]
	v_pk_mul_f32 v[46:47], v[10:11], v[40:41] op_sel_hi:[1,0]
	v_add_f32_dpp v48, v48, v48 quad_perm:[2,3,0,1] row_mask:0xf bank_mask:0xf bound_ctrl:1
	v_pk_fma_f32 v[44:45], v[94:95], v[4:5], v[44:45]
	v_pk_fma_f32 v[46:47], v[96:97], v[6:7], v[46:47]
	v_add_f32_dpp v48, v48, v48 row_half_mirror row_mask:0xf bank_mask:0xf bound_ctrl:1
	ds_read_b128 v[32:35], v50 offset:39680
	ds_read_b128 v[36:39], v50 offset:38400
	v_add_f32_dpp v48, v48, v48 row_mirror row_mask:0xf bank_mask:0xf bound_ctrl:1
	v_pk_fma_f32 v[44:45], v[12:13], v[48:49], v[44:45] op_sel_hi:[1,0,1]
	v_pk_fma_f32 v[46:47], v[14:15], v[48:49], v[46:47] op_sel_hi:[1,0,1]
	v_pk_mul_f32 v[48:49], v[44:45], v[20:21]
	v_pk_mul_f32 v[76:77], v[44:45], v[16:17]
	v_pk_fma_f32 v[48:49], v[46:47], v[22:23], v[48:49]
	v_pk_fma_f32 v[76:77], v[46:47], v[18:19], v[76:77]
	v_add_f32_e32 v48, v48, v49
	v_add_f32_e32 v68, v76, v77
	ds_read_b128 v[20:23], v50 offset:42496
	ds_read_b128 v[8:11], v50 offset:40448
	ds_read2st64_b32 v[42:43], v51 offset0:159 offset1:165
	ds_read_b128 v[4:7], v50 offset:40192
	s_waitcnt lgkmcnt(4)
	v_add_f32_dpp v48, v48, v48 quad_perm:[1,0,3,2] row_mask:0xf bank_mask:0xf bound_ctrl:1
	v_pk_mul_f32 v[94:95], v[28:29], v[40:41] op_sel:[0,1]
	v_pk_mul_f32 v[96:97], v[30:31], v[40:41] op_sel:[0,1]
	v_add_f32_dpp v48, v48, v48 quad_perm:[2,3,0,1] row_mask:0xf bank_mask:0xf bound_ctrl:1
	v_pk_fma_f32 v[94:95], v[44:45], v[24:25], v[94:95]
	v_pk_fma_f32 v[96:97], v[46:47], v[26:27], v[96:97]
	v_add_f32_dpp v48, v48, v48 row_half_mirror row_mask:0xf bank_mask:0xf bound_ctrl:1
	ds_read_b128 v[12:15], v50 offset:41216
	ds_read_b128 v[16:19], v50 offset:39936
	v_add_f32_dpp v48, v48, v48 row_mirror row_mask:0xf bank_mask:0xf bound_ctrl:1
	v_pk_fma_f32 v[94:95], v[32:33], v[48:49], v[94:95] op_sel_hi:[1,0,1]
	v_pk_fma_f32 v[96:97], v[34:35], v[48:49], v[96:97] op_sel_hi:[1,0,1]
	v_pk_mul_f32 v[48:49], v[94:95], v[0:1]
	v_pk_mul_f32 v[76:77], v[94:95], v[36:37]
	v_pk_fma_f32 v[48:49], v[96:97], v[2:3], v[48:49]
	v_pk_fma_f32 v[76:77], v[96:97], v[38:39], v[76:77]
	v_add_f32_e32 v48, v48, v49
	v_add_f32_e32 v69, v76, v77
	ds_read_b128 v[0:3], v50 offset:44032
	ds_read_b128 v[28:31], v50 offset:41984
	ds_read_b128 v[24:27], v50 offset:41728
	s_waitcnt lgkmcnt(3)
	v_add_f32_dpp v48, v48, v48 quad_perm:[1,0,3,2] row_mask:0xf bank_mask:0xf bound_ctrl:1
	v_pk_mul_f32 v[44:45], v[8:9], v[42:43] op_sel_hi:[1,0]
	v_pk_mul_f32 v[46:47], v[10:11], v[42:43] op_sel_hi:[1,0]
	v_add_f32_dpp v48, v48, v48 quad_perm:[2,3,0,1] row_mask:0xf bank_mask:0xf bound_ctrl:1
	v_pk_fma_f32 v[44:45], v[94:95], v[4:5], v[44:45]
	v_pk_fma_f32 v[46:47], v[96:97], v[6:7], v[46:47]
	v_add_f32_dpp v48, v48, v48 row_half_mirror row_mask:0xf bank_mask:0xf bound_ctrl:1
	ds_read_b128 v[32:35], v50 offset:42752
	ds_read_b128 v[36:39], v50 offset:41472
	v_add_f32_dpp v48, v48, v48 row_mirror row_mask:0xf bank_mask:0xf bound_ctrl:1
	v_pk_fma_f32 v[44:45], v[12:13], v[48:49], v[44:45] op_sel_hi:[1,0,1]
	v_pk_fma_f32 v[46:47], v[14:15], v[48:49], v[46:47] op_sel_hi:[1,0,1]
	v_pk_mul_f32 v[48:49], v[44:45], v[20:21]
	v_pk_mul_f32 v[76:77], v[44:45], v[16:17]
	v_pk_fma_f32 v[48:49], v[46:47], v[22:23], v[48:49]
	v_pk_fma_f32 v[76:77], v[46:47], v[18:19], v[76:77]
	v_add_f32_e32 v48, v48, v49
	v_add_f32_e32 v70, v76, v77
	ds_read_b128 v[20:23], v50 offset:45568
	ds_read_b128 v[8:11], v50 offset:43520
	ds_read2st64_b32 v[40:41], v51 offset0:171 offset1:177
	ds_read_b128 v[4:7], v50 offset:43264
	s_waitcnt lgkmcnt(4)
; #define LAS __attribute__((address_space(3)))
; __device__ __forceinline__ float sum16(float x) { x += dpp_f<0xB1>(x); x += dpp_f<0x4E>(x); x += dpp_f<0x141>(x); x += dpp_f<0x140>(x); return x; }
; __device__ __forceinline__ void rwkv_scan_phase(LAS unsigned char* lds, const bf16_t* RKV, const float* DEC, const float* AF, const float* k_k, const float* k_a, const float* r_k, float* BON, float* Y, int bx, const int tid) {
;     ...
;             for (int t = 0; t < SC_T; ++t) {
;                 f32x4 r4n = r4, w4n = w4, k4n = k4, a4n = a4, b4n = b4; float vvn = vv;
;                 if (t + 1 < SC_T) { const LAS unsigned char* p = base + (t + 1) * SC_TOK;
;                     r4n = *(const LAS f32x4*)(p); w4n = *(const LAS f32x4*)(p + 256); k4n = *(const LAS f32x4*)(p + 512); a4n = *(const LAS f32x4*)(p + 1024); b4n = *(const LAS f32x4*)(p + 1280);
;                     vvn = *(const LAS float*)(vbase + (t + 1) * SC_TOK); }
;                 const f32x2 a01 = {a4[0], a4[1]}, a23 = {a4[2], a4[3]}, w01 = {w4[0], w4[1]}, w23 = {w4[2], w4[3]}, b01 = {b4[0], b4[1]}, b23 = {b4[2], b4[3]}, k01 = {k4[0], k4[1]}, k23 = {k4[2], k4[3]}, r01 = {r4[0], r4[1]}, r23 = {r4[2], r4[3]};
;                 const f32x2 tsa = S01 * a01 + S23 * a23; const float sa = sum16(tsa[0] + tsa[1]);
;                 S01 = S01 * w01 + (b01 * sa + k01 * vv); S23 = S23 * w23 + (b23 * sa + k23 * vv);
;                 const f32x2 ty = S01 * r01 + S23 * r23; const float y = sum16(ty[0] + ty[1]);
	v_add_f32_dpp v48, v48, v48 quad_perm:[1,0,3,2] row_mask:0xf bank_mask:0xf bound_ctrl:1
	v_pk_mul_f32 v[94:95], v[28:29], v[42:43] op_sel:[0,1]
	v_pk_mul_f32 v[96:97], v[30:31], v[42:43] op_sel:[0,1]
	v_add_f32_dpp v48, v48, v48 quad_perm:[2,3,0,1] row_mask:0xf bank_mask:0xf bound_ctrl:1
	v_pk_fma_f32 v[94:95], v[44:45], v[24:25], v[94:95]
	v_pk_fma_f32 v[96:97], v[46:47], v[26:27], v[96:97]
	v_add_f32_dpp v48, v48, v48 row_half_mirror row_mask:0xf bank_mask:0xf bound_ctrl:1
	ds_read_b128 v[12:15], v50 offset:44288
	ds_read_b128 v[16:19], v50 offset:43008
	v_add_f32_dpp v48, v48, v48 row_mirror row_mask:0xf bank_mask:0xf bound_ctrl:1
	v_pk_fma_f32 v[94:95], v[32:33], v[48:49], v[94:95] op_sel_hi:[1,0,1]
	v_pk_fma_f32 v[96:97], v[34:35], v[48:49], v[96:97] op_sel_hi:[1,0,1]
	v_pk_mul_f32 v[48:49], v[94:95], v[0:1]
	v_pk_mul_f32 v[76:77], v[94:95], v[36:37]
	v_pk_fma_f32 v[48:49], v[96:97], v[2:3], v[48:49]
	v_pk_fma_f32 v[76:77], v[96:97], v[38:39], v[76:77]
	v_add_f32_e32 v48, v48, v49
	v_add_f32_e32 v71, v76, v77
	ds_read_b128 v[0:3], v50 offset:47104
	ds_read_b128 v[28:31], v50 offset:45056
	ds_read_b128 v[24:27], v50 offset:44800
	s_waitcnt lgkmcnt(3)
	v_add_f32_dpp v48, v48, v48 quad_perm:[1,0,3,2] row_mask:0xf bank_mask:0xf bound_ctrl:1
	v_pk_mul_f32 v[44:45], v[8:9], v[40:41] op_sel_hi:[1,0]
	v_pk_mul_f32 v[46:47], v[10:11], v[40:41] op_sel_hi:[1,0]
	v_add_f32_dpp v48, v48, v48 quad_perm:[2,3,0,1] row_mask:0xf bank_mask:0xf bound_ctrl:1
	v_pk_fma_f32 v[44:45], v[94:95], v[4:5], v[44:45]
	v_pk_fma_f32 v[46:47], v[96:97], v[6:7], v[46:47]
	v_add_f32_dpp v48, v48, v48 row_half_mirror row_mask:0xf bank_mask:0xf bound_ctrl:1
	ds_read_b128 v[32:35], v50 offset:45824
	ds_read_b128 v[36:39], v50 offset:44544
	v_add_f32_dpp v48, v48, v48 row_mirror row_mask:0xf bank_mask:0xf bound_ctrl:1
	v_pk_fma_f32 v[44:45], v[12:13], v[48:49], v[44:45] op_sel_hi:[1,0,1]
	v_pk_fma_f32 v[46:47], v[14:15], v[48:49], v[46:47] op_sel_hi:[1,0,1]
	v_pk_mul_f32 v[48:49], v[44:45], v[20:21]
	v_pk_mul_f32 v[76:77], v[44:45], v[16:17]
	v_pk_fma_f32 v[48:49], v[46:47], v[22:23], v[48:49]
	v_pk_fma_f32 v[76:77], v[46:47], v[18:19], v[76:77]
	v_add_f32_e32 v48, v48, v49
	v_add_f32_e32 v72, v76, v77
	ds_read_b128 v[20:23], v50 offset:48640
	ds_read_b128 v[8:11], v50 offset:46592
	ds_read2st64_b32 v[42:43], v51 offset0:183 offset1:189
	ds_read_b128 v[4:7], v50 offset:46336
	s_waitcnt lgkmcnt(4)
	v_add_f32_dpp v48, v48, v48 quad_perm:[1,0,3,2] row_mask:0xf bank_mask:0xf bound_ctrl:1
	v_pk_mul_f32 v[94:95], v[28:29], v[40:41] op_sel:[0,1]
	v_pk_mul_f32 v[96:97], v[30:31], v[40:41] op_sel:[0,1]
	v_add_f32_dpp v48, v48, v48 quad_perm:[2,3,0,1] row_mask:0xf bank_mask:0xf bound_ctrl:1
	v_pk_fma_f32 v[94:95], v[44:45], v[24:25], v[94:95]
	v_pk_fma_f32 v[96:97], v[46:47], v[26:27], v[96:97]
	v_add_f32_dpp v48, v48, v48 row_half_mirror row_mask:0xf bank_mask:0xf bound_ctrl:1
	ds_read_b128 v[12:15], v50 offset:47360
	ds_read_b128 v[16:19], v50 offset:46080
	v_add_f32_dpp v48, v48, v48 row_mirror row_mask:0xf bank_mask:0xf bound_ctrl:1
	v_pk_fma_f32 v[94:95], v[32:33], v[48:49], v[94:95] op_sel_hi:[1,0,1]
	v_pk_fma_f32 v[96:97], v[34:35], v[48:49], v[96:97] op_sel_hi:[1,0,1]
	v_pk_mul_f32 v[48:49], v[94:95], v[0:1]
	v_pk_mul_f32 v[76:77], v[94:95], v[36:37]
	v_pk_fma_f32 v[48:49], v[96:97], v[2:3], v[48:49]
	v_pk_fma_f32 v[76:77], v[96:97], v[38:39], v[76:77]
	v_add_f32_e32 v48, v48, v49
	v_add_f32_e32 v73, v76, v77
	ds_read_b128 v[28:31], v50 offset:48128
	ds_read_b128 v[24:27], v50 offset:47872
	s_waitcnt lgkmcnt(2)
; __device__ __forceinline__ float sum16(float x) { x += dpp_f<0xB1>(x); x += dpp_f<0x4E>(x); x += dpp_f<0x141>(x); x += dpp_f<0x140>(x); return x; }
; __device__ __forceinline__ void rwkv_scan_phase(LAS unsigned char* lds, const bf16_t* RKV, const float* DEC, const float* AF, const float* k_k, const float* k_a, const float* r_k, float* BON, float* Y, int bx, const int tid) {
;     ...
;                 const f32x2 tsa = S01 * a01 + S23 * a23; const float sa = sum16(tsa[0] + tsa[1]);
;                 S01 = S01 * w01 + (b01 * sa + k01 * vv); S23 = S23 * w23 + (b23 * sa + k23 * vv);
;                 const f32x2 ty = S01 * r01 + S23 * r23; const float y = sum16(ty[0] + ty[1]);
;                 ykeep = ((lane & 15) == (t & 15)) ? y : ykeep;
;                 if ((t & 15) == 15) yp[(size_t)(c * SC_T + (t - 15) + (lane & 15)) * 2048] = ykeep;
;                 r4 = r4n; w4 = w4n; k4 = k4n; a4 = a4n; b4 = b4n; vv = vvn;
	v_add_f32_dpp v48, v48, v48 quad_perm:[1,0,3,2] row_mask:0xf bank_mask:0xf bound_ctrl:1
	v_pk_mul_f32 v[44:45], v[8:9], v[42:43] op_sel_hi:[1,0]
	v_pk_mul_f32 v[46:47], v[10:11], v[42:43] op_sel_hi:[1,0]
	v_add_f32_dpp v48, v48, v48 quad_perm:[2,3,0,1] row_mask:0xf bank_mask:0xf bound_ctrl:1
	v_pk_fma_f32 v[44:45], v[94:95], v[4:5], v[44:45]
	v_pk_fma_f32 v[46:47], v[96:97], v[6:7], v[46:47]
	v_add_f32_dpp v48, v48, v48 row_half_mirror row_mask:0xf bank_mask:0xf bound_ctrl:1
	ds_read_b128 v[32:35], v50 offset:48896
	ds_read_b128 v[36:39], v50 offset:47616
	v_add_f32_dpp v48, v48, v48 row_mirror row_mask:0xf bank_mask:0xf bound_ctrl:1
	v_pk_fma_f32 v[44:45], v[12:13], v[48:49], v[44:45] op_sel_hi:[1,0,1]
	v_pk_fma_f32 v[46:47], v[14:15], v[48:49], v[46:47] op_sel_hi:[1,0,1]
	v_pk_mul_f32 v[48:49], v[44:45], v[20:21]
	v_pk_mul_f32 v[76:77], v[44:45], v[16:17]
	v_pk_fma_f32 v[48:49], v[46:47], v[22:23], v[48:49]
	v_pk_fma_f32 v[76:77], v[46:47], v[18:19], v[76:77]
	v_add_f32_e32 v48, v48, v49
	v_add_f32_e32 v74, v76, v77
	s_waitcnt lgkmcnt(0)
	s_nop 0
	v_add_f32_dpp v48, v48, v48 quad_perm:[1,0,3,2] row_mask:0xf bank_mask:0xf bound_ctrl:1
	v_pk_mul_f32 v[94:95], v[28:29], v[42:43] op_sel:[0,1]
	v_pk_mul_f32 v[96:97], v[30:31], v[42:43] op_sel:[0,1]
	v_add_f32_dpp v48, v48, v48 quad_perm:[2,3,0,1] row_mask:0xf bank_mask:0xf bound_ctrl:1
	v_pk_fma_f32 v[94:95], v[44:45], v[24:25], v[94:95]
	v_pk_fma_f32 v[96:97], v[46:47], v[26:27], v[96:97]
	v_add_f32_dpp v48, v48, v48 row_half_mirror row_mask:0xf bank_mask:0xf bound_ctrl:1
	s_nop 1
	v_add_f32_dpp v48, v48, v48 row_mirror row_mask:0xf bank_mask:0xf bound_ctrl:1
	v_pk_fma_f32 v[94:95], v[32:33], v[48:49], v[94:95] op_sel_hi:[1,0,1]
	v_pk_fma_f32 v[96:97], v[34:35], v[48:49], v[96:97] op_sel_hi:[1,0,1]
	v_pk_mul_f32 v[76:77], v[94:95], v[36:37]
	v_pk_fma_f32 v[76:77], v[96:97], v[38:39], v[76:77]
	v_add_f32_e32 v75, v76, v77
	v_add_f32_dpp v60, v60, v60 row_mirror row_mask:0xf bank_mask:0x3 bound_ctrl:1
	v_add_f32_dpp v60, v68, v68 row_mirror row_mask:0xf bank_mask:0xc bound_ctrl:1
	v_add_f32_dpp v61, v61, v61 row_mirror row_mask:0xf bank_mask:0x3 bound_ctrl:1
	v_add_f32_dpp v61, v69, v69 row_mirror row_mask:0xf bank_mask:0xc bound_ctrl:1
	v_add_f32_dpp v62, v62, v62 row_mirror row_mask:0xf bank_mask:0x3 bound_ctrl:1
	v_add_f32_dpp v62, v70, v70 row_mirror row_mask:0xf bank_mask:0xc bound_ctrl:1
	v_add_f32_dpp v63, v63, v63 row_mirror row_mask:0xf bank_mask:0x3 bound_ctrl:1
	v_add_f32_dpp v63, v71, v71 row_mirror row_mask:0xf bank_mask:0xc bound_ctrl:1
	v_add_f32_dpp v64, v64, v64 row_mirror row_mask:0xf bank_mask:0x3 bound_ctrl:1
	v_add_f32_dpp v64, v72, v72 row_mirror row_mask:0xf bank_mask:0xc bound_ctrl:1
	v_add_f32_dpp v65, v65, v65 row_mirror row_mask:0xf bank_mask:0x3 bound_ctrl:1
	v_add_f32_dpp v65, v73, v73 row_mirror row_mask:0xf bank_mask:0xc bound_ctrl:1
	v_add_f32_dpp v66, v66, v66 row_mirror row_mask:0xf bank_mask:0x3 bound_ctrl:1
	v_add_f32_dpp v66, v74, v74 row_mirror row_mask:0xf bank_mask:0xc bound_ctrl:1
	v_add_f32_dpp v67, v67, v67 row_mirror row_mask:0xf bank_mask:0x3 bound_ctrl:1
	v_add_f32_dpp v67, v75, v75 row_mirror row_mask:0xf bank_mask:0xc bound_ctrl:1
	v_add_f32_dpp v60, v60, v60 row_half_mirror row_mask:0xf bank_mask:0x5 bound_ctrl:1
	v_add_f32_dpp v60, v64, v64 row_half_mirror row_mask:0xf bank_mask:0xa bound_ctrl:1
	v_add_f32_dpp v61, v61, v61 row_half_mirror row_mask:0xf bank_mask:0x5 bound_ctrl:1
	v_add_f32_dpp v61, v65, v65 row_half_mirror row_mask:0xf bank_mask:0xa bound_ctrl:1
	v_add_f32_dpp v62, v62, v62 row_half_mirror row_mask:0xf bank_mask:0x5 bound_ctrl:1
	v_add_f32_dpp v62, v66, v66 row_half_mirror row_mask:0xf bank_mask:0xa bound_ctrl:1
	v_add_f32_dpp v63, v63, v63 row_half_mirror row_mask:0xf bank_mask:0x5 bound_ctrl:1
	v_add_f32_dpp v63, v67, v67 row_half_mirror row_mask:0xf bank_mask:0xa bound_ctrl:1
	v_cndmask_b32_e64 v76, v62, v60, s[46:47]
	v_cndmask_b32_e64 v77, v63, v61, s[46:47]
	v_cndmask_b32_e64 v78, v60, v62, s[46:47]
	v_cndmask_b32_e64 v79, v61, v63, s[46:47]
	s_nop 0
	v_add_f32_dpp v60, v76, v78 quad_perm:[2,3,0,1] row_mask:0xf bank_mask:0xf bound_ctrl:1
	v_add_f32_dpp v61, v77, v79 quad_perm:[2,3,0,1] row_mask:0xf bank_mask:0xf bound_ctrl:1
	v_cndmask_b32_e64 v76, v61, v60, s[40:41]
	v_cndmask_b32_e64 v78, v60, v61, s[40:41]
	v_lshl_add_u64 v[52:53], v[92:93], 0, s[76:77]
	s_nop 0
	v_add_f32_dpp v60, v76, v78 quad_perm:[1,0,3,2] row_mask:0xf bank_mask:0xf bound_ctrl:1
	global_store_dword v[52:53], v60, off
	s_branch .LBB0_223
